# barrier 2 shortened on both sides: last P1 unit's epilogue stores write-through (little dirty L2 for the leader's write-back) + dt job single-round loads and batched row scales + barrier waits polling
# baseline (speedup 1.0000x reference)
; __device__ __forceinline__ unsigned cvt_pk_bf16(float lo, float hi) { unsigned r; asm volatile("v_cvt_pk_bf16_f32 %0, %1, %2" : "=v"(r) : "v"(lo), "v"(hi)); return r; }
;     __device__ __forceinline__ void operator()(const f32x4 (&acc)[2][2][4][2], const Unit& u, int wr, int wc, int fr, int fq) const {
;     ...
;                 const int row = row0 + ai * HALF + m * 16; const float rsv = rs[row] * sc;
;                 f32x4 cs = (f32x4){1.f, 1.f, 1.f, 1.f}, sn = (f32x4){0.f, 0.f, 0.f, 0.f};
;                 if (ropel) { const int t = row & 8191; cs = *(const f32x4*)(rope + t * 8 + 4 * fq); sn = *(const f32x4*)(rope + 65536 + t * 8 + 4 * fq); }
;                 bf16_t* rowp = base + (size_t)row * ldc + col0;
; #pragma unroll
;                 for (int bj = 0; bj < 2; ++bj) {
;                     f32x4 v0 = acc[ai][bj][m][0] * rsv, v1 = acc[ai][bj][m][1] * rsv;
;                     if (dorope) {
;                         const f32x4 a0 = v0, a1 = v1;
;                         v0[0] = a0[0] * cs[0] - a0[1] * sn[0]; v0[1] = a0[1] * cs[0] + a0[0] * sn[0];
;                         v0[2] = a0[2] * cs[1] - a0[3] * sn[1]; v0[3] = a0[3] * cs[1] + a0[2] * sn[1];
;                         v1[0] = a1[0] * cs[2] - a1[1] * sn[2]; v1[1] = a1[1] * cs[2] + a1[0] * sn[2];
;                         v1[2] = a1[2] * cs[3] - a1[3] * sn[3]; v1[3] = a1[3] * cs[3] + a1[2] * sn[3];
;                     }
;                     if (dosilu) {
; #pragma unroll
;                         for (int e_ = 0; e_ < 4; ++e_) { v0[e_] = v0[e_] * __builtin_amdgcn_rcpf(1.f + __builtin_amdgcn_exp2f(v0[e_] * -1.4426950408889634f)); v1[e_] = v1[e_] * __builtin_amdgcn_rcpf(1.f + __builtin_amdgcn_exp2f(v1[e_] * -1.4426950408889634f)); }
;                     }
;                     u32x4 w; w.x = cvt_pk_bf16(v0[0], v0[1]); w.y = cvt_pk_bf16(v0[2], v0[3]); w.z = cvt_pk_bf16(v1[0], v1[1]); w.w = cvt_pk_bf16(v1[2], v1[3]);
;                     *(u32x4*)(rowp + bj * HALF) = w;
.LBB0_253:
	v_add_u32_e32 v162, s83, v170
	v_ashrrev_i32_e32 v163, 31, v162
	v_lshl_add_u64 v[162:163], v[162:163], 1, s[90:91]
	v_mul_lo_u32 v144, s69, v158
	v_mul_lo_u32 v159, s68, v159
	v_mad_u64_u32 v[166:167], s[90:91], s68, v158, 0
	v_mov_b32_e32 v165, v164
	v_add3_u32 v167, v167, v159, v144
	v_cvt_pk_bf16_f32 v124, v124, v125
	v_cvt_pk_bf16_f32 v125, v126, v127
	v_cvt_pk_bf16_f32 v126, v120, v121
	v_mov_b32_e32 v120, v164
	v_mov_b32_e32 v121, v164
	v_lshl_add_u64 v[166:167], v[166:167], 1, v[162:163]
	v_pk_mul_f32 v[118:119], v[118:119], v[120:121]
	v_pk_mul_f32 v[116:117], v[116:117], v[164:165]
	v_pk_mul_f32 v[114:115], v[114:115], v[120:121]
	s_and_b64 vcc, exec, s[2:3]
	v_pk_mul_f32 v[112:113], v[112:113], v[164:165]
	v_cvt_pk_bf16_f32 v127, v122, v123
	s_cmp_eq_u64 s[0:1], 0
	s_cbranch_scc1 .Lwtp1_0
	global_store_dwordx4 v[166:167], v[124:127], off
	s_branch .Lwtp1d_0
.Lwtp1_0:
	global_store_dwordx4 v[166:167], v[124:127], off sc1
.Lwtp1d_0:
	s_cbranch_vccnz .LBB0_255
	v_pk_mul_f32 v[122:123], v[116:117], v[132:133] op_sel:[1,0] op_sel_hi:[0,0]
	v_pk_fma_f32 v[120:121], v[116:117], v[128:129], v[122:123] op_sel_hi:[1,0,1] neg_lo:[0,0,1] neg_hi:[0,0,1]
	v_pk_fma_f32 v[116:117], v[116:117], v[128:129], v[122:123] op_sel_hi:[1,0,1]
	v_mov_b32_e32 v132, v129
	v_mul_f32_e32 v116, v119, v133
	v_pk_fma_f32 v[122:123], v[118:119], v[132:133], v[116:117] op_sel_hi:[1,1,0] neg_lo:[0,0,1] neg_hi:[0,0,1]
	v_mov_b32_e32 v128, v133
	v_mul_f32_e32 v116, v119, v129
	v_pk_fma_f32 v[118:119], v[118:119], v[128:129], v[116:117] op_sel_hi:[1,1,0]
	v_mov_b32_e32 v121, v117
	v_pk_mul_f32 v[116:117], v[112:113], v[134:135] op_sel:[1,0] op_sel_hi:[0,0]
	v_pk_fma_f32 v[124:125], v[112:113], v[130:131], v[116:117] op_sel_hi:[1,0,1] neg_lo:[0,0,1] neg_hi:[0,0,1]
	v_pk_fma_f32 v[112:113], v[112:113], v[130:131], v[116:117] op_sel_hi:[1,0,1]
	v_mov_b32_e32 v134, v131
	v_mul_f32_e32 v112, v115, v135
	v_pk_fma_f32 v[126:127], v[114:115], v[134:135], v[112:113] op_sel_hi:[1,1,0] neg_lo:[0,0,1] neg_hi:[0,0,1]
	v_mov_b32_e32 v130, v135
	v_mul_f32_e32 v112, v115, v131
	v_pk_fma_f32 v[114:115], v[114:115], v[130:131], v[112:113] op_sel_hi:[1,1,0]
	v_mov_b32_e32 v125, v113
	v_mov_b32_e32 v123, v118
	v_mov_b32_e32 v127, v114
	v_mov_b64_e32 v[116:117], v[120:121]
	v_mov_b64_e32 v[112:113], v[124:125]
	v_mov_b64_e32 v[118:119], v[122:123]
	v_mov_b64_e32 v[114:115], v[126:127]

; __device__ __forceinline__ unsigned cvt_pk_bf16(float lo, float hi) { unsigned r; asm volatile("v_cvt_pk_bf16_f32 %0, %1, %2" : "=v"(r) : "v"(lo), "v"(hi)); return r; }
;     __device__ __forceinline__ void operator()(const f32x4 (&acc)[2][2][4][2], const Unit& u, int wr, int wc, int fr, int fq) const {
;     ...
;                 const int row = row0 + ai * HALF + m * 16; const float rsv = rs[row] * sc;
;                 f32x4 cs = (f32x4){1.f, 1.f, 1.f, 1.f}, sn = (f32x4){0.f, 0.f, 0.f, 0.f};
;                 if (ropel) { const int t = row & 8191; cs = *(const f32x4*)(rope + t * 8 + 4 * fq); sn = *(const f32x4*)(rope + 65536 + t * 8 + 4 * fq); }
;                 bf16_t* rowp = base + (size_t)row * ldc + col0;
; #pragma unroll
;                 for (int bj = 0; bj < 2; ++bj) {
;                     f32x4 v0 = acc[ai][bj][m][0] * rsv, v1 = acc[ai][bj][m][1] * rsv;
;                     if (dorope) {
;                         const f32x4 a0 = v0, a1 = v1;
;                         v0[0] = a0[0] * cs[0] - a0[1] * sn[0]; v0[1] = a0[1] * cs[0] + a0[0] * sn[0];
;                         v0[2] = a0[2] * cs[1] - a0[3] * sn[1]; v0[3] = a0[3] * cs[1] + a0[2] * sn[1];
;                         v1[0] = a1[0] * cs[2] - a1[1] * sn[2]; v1[1] = a1[1] * cs[2] + a1[0] * sn[2];
;                         v1[2] = a1[2] * cs[3] - a1[3] * sn[3]; v1[3] = a1[3] * cs[3] + a1[2] * sn[3];
;                     }
;                     if (dosilu) {
; #pragma unroll
;                         for (int e_ = 0; e_ < 4; ++e_) { v0[e_] = v0[e_] * __builtin_amdgcn_rcpf(1.f + __builtin_amdgcn_exp2f(v0[e_] * -1.4426950408889634f)); v1[e_] = v1[e_] * __builtin_amdgcn_rcpf(1.f + __builtin_amdgcn_exp2f(v1[e_] * -1.4426950408889634f)); }
;                     }
;                     u32x4 w; w.x = cvt_pk_bf16(v0[0], v0[1]); w.y = cvt_pk_bf16(v0[2], v0[3]); w.z = cvt_pk_bf16(v1[0], v1[1]); w.w = cvt_pk_bf16(v1[2], v1[3]);
;                     *(u32x4*)(rowp + bj * HALF) = w;
.LBB0_257:
	v_or_b32_e32 v120, 16, v158
	v_ashrrev_i32_e32 v121, 31, v120
	v_cvt_pk_bf16_f32 v116, v116, v117
	v_cvt_pk_bf16_f32 v117, v118, v119
	v_cvt_pk_bf16_f32 v118, v112, v113
	v_cvt_pk_bf16_f32 v119, v114, v115
	s_cmp_eq_u64 s[0:1], 0
	s_cbranch_scc1 .Lwtp1_1
	global_store_dwordx4 v[166:167], v[116:119], off offset:256
	s_branch .Lwtp1d_1
.Lwtp1_1:
	global_store_dwordx4 v[166:167], v[116:119], off offset:256 sc1
.Lwtp1d_1:
	v_lshl_add_u64 v[112:113], v[120:121], 2, s[6:7]
	v_mov_b32_e32 v122, v231
	v_mov_b32_e32 v116, 0
	v_mov_b32_e32 v112, 1.0
	v_mov_b32_e32 v113, 1.0
	v_mov_b32_e32 v114, 1.0
	v_mov_b32_e32 v115, 1.0
	v_mov_b32_e32 v117, 0
	v_mov_b32_e32 v118, 0
	v_mov_b32_e32 v119, 0
	s_and_saveexec_b64 s[90:91], s[88:89]
	s_cbranch_execz .LBB0_259
	v_lshlrev_b32_e32 v112, 5, v120
	v_and_b32_e32 v144, 0x3fbe0, v112
	v_lshl_add_u64 v[116:117], v[148:149], 0, v[144:145]
	v_lshl_add_u64 v[112:113], v[146:147], 0, v[144:145]
	global_load_dwordx4 v[112:115], v[112:113], off
	s_nop 0
	global_load_dwordx4 v[116:119], v[116:117], off
	s_waitcnt vmcnt(0)

; __device__ __forceinline__ unsigned cvt_pk_bf16(float lo, float hi) { unsigned r; asm volatile("v_cvt_pk_bf16_f32 %0, %1, %2" : "=v"(r) : "v"(lo), "v"(hi)); return r; }
;     __device__ __forceinline__ void operator()(const f32x4 (&acc)[2][2][4][2], const Unit& u, int wr, int wc, int fr, int fq) const {
;     ...
;                 const int row = row0 + ai * HALF + m * 16; const float rsv = rs[row] * sc;
;                 f32x4 cs = (f32x4){1.f, 1.f, 1.f, 1.f}, sn = (f32x4){0.f, 0.f, 0.f, 0.f};
;                 if (ropel) { const int t = row & 8191; cs = *(const f32x4*)(rope + t * 8 + 4 * fq); sn = *(const f32x4*)(rope + 65536 + t * 8 + 4 * fq); }
;                 bf16_t* rowp = base + (size_t)row * ldc + col0;
; #pragma unroll
;                 for (int bj = 0; bj < 2; ++bj) {
;                     f32x4 v0 = acc[ai][bj][m][0] * rsv, v1 = acc[ai][bj][m][1] * rsv;
;                     if (dorope) {
;                         const f32x4 a0 = v0, a1 = v1;
;                         v0[0] = a0[0] * cs[0] - a0[1] * sn[0]; v0[1] = a0[1] * cs[0] + a0[0] * sn[0];
;                         v0[2] = a0[2] * cs[1] - a0[3] * sn[1]; v0[3] = a0[3] * cs[1] + a0[2] * sn[1];
;                         v1[0] = a1[0] * cs[2] - a1[1] * sn[2]; v1[1] = a1[1] * cs[2] + a1[0] * sn[2];
;                         v1[2] = a1[2] * cs[3] - a1[3] * sn[3]; v1[3] = a1[3] * cs[3] + a1[2] * sn[3];
;                     }
;                     if (dosilu) {
; #pragma unroll
;                         for (int e_ = 0; e_ < 4; ++e_) { v0[e_] = v0[e_] * __builtin_amdgcn_rcpf(1.f + __builtin_amdgcn_exp2f(v0[e_] * -1.4426950408889634f)); v1[e_] = v1[e_] * __builtin_amdgcn_rcpf(1.f + __builtin_amdgcn_exp2f(v1[e_] * -1.4426950408889634f)); }
;                     }
;                     u32x4 w; w.x = cvt_pk_bf16(v0[0], v0[1]); w.y = cvt_pk_bf16(v0[2], v0[3]); w.z = cvt_pk_bf16(v1[0], v1[1]); w.w = cvt_pk_bf16(v1[2], v1[3]);
;                     *(u32x4*)(rowp + bj * HALF) = w;
.LBB0_263:
	v_mul_lo_u32 v124, s69, v120
	v_mul_lo_u32 v125, s68, v121
	v_mad_u64_u32 v[120:121], s[90:91], s68, v120, 0
	v_mov_b32_e32 v123, v122
	v_add3_u32 v121, v121, v125, v124
	v_cvt_pk_bf16_f32 v108, v108, v109
	v_cvt_pk_bf16_f32 v109, v110, v111
	v_cvt_pk_bf16_f32 v110, v104, v105
	v_mov_b32_e32 v104, v122
	v_mov_b32_e32 v105, v122
	v_lshl_add_u64 v[120:121], v[120:121], 1, v[162:163]
	v_pk_mul_f32 v[102:103], v[102:103], v[104:105]
	v_pk_mul_f32 v[100:101], v[100:101], v[122:123]
	v_pk_mul_f32 v[98:99], v[98:99], v[104:105]
	s_and_b64 vcc, exec, s[2:3]
	v_pk_mul_f32 v[96:97], v[96:97], v[122:123]
	v_cvt_pk_bf16_f32 v111, v106, v107
	s_cmp_eq_u64 s[0:1], 0
	s_cbranch_scc1 .Lwtp1_2
	global_store_dwordx4 v[120:121], v[108:111], off
	s_branch .Lwtp1d_2
.Lwtp1_2:
	global_store_dwordx4 v[120:121], v[108:111], off sc1
.Lwtp1d_2:
	s_cbranch_vccnz .LBB0_265
	v_pk_mul_f32 v[106:107], v[100:101], v[116:117] op_sel:[1,0] op_sel_hi:[0,0]
	v_pk_fma_f32 v[104:105], v[100:101], v[112:113], v[106:107] op_sel_hi:[1,0,1] neg_lo:[0,0,1] neg_hi:[0,0,1]
	v_pk_fma_f32 v[100:101], v[100:101], v[112:113], v[106:107] op_sel_hi:[1,0,1]
	v_mov_b32_e32 v116, v113
	v_mul_f32_e32 v100, v103, v117
	v_pk_fma_f32 v[106:107], v[102:103], v[116:117], v[100:101] op_sel_hi:[1,1,0] neg_lo:[0,0,1] neg_hi:[0,0,1]
	v_mov_b32_e32 v112, v117
	v_mul_f32_e32 v100, v103, v113
	v_pk_fma_f32 v[102:103], v[102:103], v[112:113], v[100:101] op_sel_hi:[1,1,0]
	v_mov_b32_e32 v105, v101
	v_pk_mul_f32 v[100:101], v[96:97], v[118:119] op_sel:[1,0] op_sel_hi:[0,0]
	v_pk_fma_f32 v[108:109], v[96:97], v[114:115], v[100:101] op_sel_hi:[1,0,1] neg_lo:[0,0,1] neg_hi:[0,0,1]
	v_pk_fma_f32 v[96:97], v[96:97], v[114:115], v[100:101] op_sel_hi:[1,0,1]
	v_mov_b32_e32 v118, v115
	v_mul_f32_e32 v96, v99, v119
	v_pk_fma_f32 v[110:111], v[98:99], v[118:119], v[96:97] op_sel_hi:[1,1,0] neg_lo:[0,0,1] neg_hi:[0,0,1]
	v_mov_b32_e32 v114, v119
	v_mul_f32_e32 v96, v99, v115
	v_pk_fma_f32 v[98:99], v[98:99], v[114:115], v[96:97] op_sel_hi:[1,1,0]
	v_mov_b32_e32 v109, v97
	v_mov_b32_e32 v107, v102
	v_mov_b32_e32 v111, v98
	v_mov_b64_e32 v[100:101], v[104:105]
	v_mov_b64_e32 v[96:97], v[108:109]
	v_mov_b64_e32 v[102:103], v[106:107]
	v_mov_b64_e32 v[98:99], v[110:111]

; __device__ __forceinline__ unsigned cvt_pk_bf16(float lo, float hi) { unsigned r; asm volatile("v_cvt_pk_bf16_f32 %0, %1, %2" : "=v"(r) : "v"(lo), "v"(hi)); return r; }
;     __device__ __forceinline__ void operator()(const f32x4 (&acc)[2][2][4][2], const Unit& u, int wr, int wc, int fr, int fq) const {
;     ...
;                 const int row = row0 + ai * HALF + m * 16; const float rsv = rs[row] * sc;
;                 f32x4 cs = (f32x4){1.f, 1.f, 1.f, 1.f}, sn = (f32x4){0.f, 0.f, 0.f, 0.f};
;                 if (ropel) { const int t = row & 8191; cs = *(const f32x4*)(rope + t * 8 + 4 * fq); sn = *(const f32x4*)(rope + 65536 + t * 8 + 4 * fq); }
;                 bf16_t* rowp = base + (size_t)row * ldc + col0;
; #pragma unroll
;                 for (int bj = 0; bj < 2; ++bj) {
;                     f32x4 v0 = acc[ai][bj][m][0] * rsv, v1 = acc[ai][bj][m][1] * rsv;
;                     if (dorope) {
;                         const f32x4 a0 = v0, a1 = v1;
;                         v0[0] = a0[0] * cs[0] - a0[1] * sn[0]; v0[1] = a0[1] * cs[0] + a0[0] * sn[0];
;                         v0[2] = a0[2] * cs[1] - a0[3] * sn[1]; v0[3] = a0[3] * cs[1] + a0[2] * sn[1];
;                         v1[0] = a1[0] * cs[2] - a1[1] * sn[2]; v1[1] = a1[1] * cs[2] + a1[0] * sn[2];
;                         v1[2] = a1[2] * cs[3] - a1[3] * sn[3]; v1[3] = a1[3] * cs[3] + a1[2] * sn[3];
;                     }
;                     if (dosilu) {
; #pragma unroll
;                         for (int e_ = 0; e_ < 4; ++e_) { v0[e_] = v0[e_] * __builtin_amdgcn_rcpf(1.f + __builtin_amdgcn_exp2f(v0[e_] * -1.4426950408889634f)); v1[e_] = v1[e_] * __builtin_amdgcn_rcpf(1.f + __builtin_amdgcn_exp2f(v1[e_] * -1.4426950408889634f)); }
;                     }
;                     u32x4 w; w.x = cvt_pk_bf16(v0[0], v0[1]); w.y = cvt_pk_bf16(v0[2], v0[3]); w.z = cvt_pk_bf16(v1[0], v1[1]); w.w = cvt_pk_bf16(v1[2], v1[3]);
;                     *(u32x4*)(rowp + bj * HALF) = w;
.LBB0_267:
	v_or_b32_e32 v104, 32, v158
	v_ashrrev_i32_e32 v105, 31, v104
	v_cvt_pk_bf16_f32 v100, v100, v101
	v_cvt_pk_bf16_f32 v101, v102, v103
	v_cvt_pk_bf16_f32 v102, v96, v97
	v_cvt_pk_bf16_f32 v103, v98, v99
	s_cmp_eq_u64 s[0:1], 0
	s_cbranch_scc1 .Lwtp1_3
	global_store_dwordx4 v[120:121], v[100:103], off offset:256
	s_branch .Lwtp1d_3
.Lwtp1_3:
	global_store_dwordx4 v[120:121], v[100:103], off offset:256 sc1
.Lwtp1d_3:
	v_lshl_add_u64 v[96:97], v[104:105], 2, s[6:7]
	v_mov_b32_e32 v106, v232
	v_mov_b32_e32 v100, 0
	v_mov_b32_e32 v96, 1.0
	v_mov_b32_e32 v97, 1.0
	v_mov_b32_e32 v98, 1.0
	v_mov_b32_e32 v99, 1.0
	v_mov_b32_e32 v101, 0
	v_mov_b32_e32 v102, 0
	v_mov_b32_e32 v103, 0
	s_and_saveexec_b64 s[90:91], s[88:89]
	s_cbranch_execz .LBB0_269
	v_lshlrev_b32_e32 v96, 5, v104
	v_and_b32_e32 v144, 0x3fde0, v96
	v_lshl_add_u64 v[100:101], v[148:149], 0, v[144:145]
	v_lshl_add_u64 v[96:97], v[146:147], 0, v[144:145]
	global_load_dwordx4 v[96:99], v[96:97], off
	s_nop 0
	global_load_dwordx4 v[100:103], v[100:101], off
	s_waitcnt vmcnt(0)

; __device__ __forceinline__ unsigned cvt_pk_bf16(float lo, float hi) { unsigned r; asm volatile("v_cvt_pk_bf16_f32 %0, %1, %2" : "=v"(r) : "v"(lo), "v"(hi)); return r; }
;     __device__ __forceinline__ void operator()(const f32x4 (&acc)[2][2][4][2], const Unit& u, int wr, int wc, int fr, int fq) const {
;     ...
;                 const int row = row0 + ai * HALF + m * 16; const float rsv = rs[row] * sc;
;                 f32x4 cs = (f32x4){1.f, 1.f, 1.f, 1.f}, sn = (f32x4){0.f, 0.f, 0.f, 0.f};
;                 if (ropel) { const int t = row & 8191; cs = *(const f32x4*)(rope + t * 8 + 4 * fq); sn = *(const f32x4*)(rope + 65536 + t * 8 + 4 * fq); }
;                 bf16_t* rowp = base + (size_t)row * ldc + col0;
; #pragma unroll
;                 for (int bj = 0; bj < 2; ++bj) {
;                     f32x4 v0 = acc[ai][bj][m][0] * rsv, v1 = acc[ai][bj][m][1] * rsv;
;                     if (dorope) {
;                         const f32x4 a0 = v0, a1 = v1;
;                         v0[0] = a0[0] * cs[0] - a0[1] * sn[0]; v0[1] = a0[1] * cs[0] + a0[0] * sn[0];
;                         v0[2] = a0[2] * cs[1] - a0[3] * sn[1]; v0[3] = a0[3] * cs[1] + a0[2] * sn[1];
;                         v1[0] = a1[0] * cs[2] - a1[1] * sn[2]; v1[1] = a1[1] * cs[2] + a1[0] * sn[2];
;                         v1[2] = a1[2] * cs[3] - a1[3] * sn[3]; v1[3] = a1[3] * cs[3] + a1[2] * sn[3];
;                     }
;                     if (dosilu) {
; #pragma unroll
;                         for (int e_ = 0; e_ < 4; ++e_) { v0[e_] = v0[e_] * __builtin_amdgcn_rcpf(1.f + __builtin_amdgcn_exp2f(v0[e_] * -1.4426950408889634f)); v1[e_] = v1[e_] * __builtin_amdgcn_rcpf(1.f + __builtin_amdgcn_exp2f(v1[e_] * -1.4426950408889634f)); }
;                     }
;                     u32x4 w; w.x = cvt_pk_bf16(v0[0], v0[1]); w.y = cvt_pk_bf16(v0[2], v0[3]); w.z = cvt_pk_bf16(v1[0], v1[1]); w.w = cvt_pk_bf16(v1[2], v1[3]);
;                     *(u32x4*)(rowp + bj * HALF) = w;
.LBB0_273:
	v_mul_lo_u32 v108, s69, v104
	v_mul_lo_u32 v109, s68, v105
	v_mad_u64_u32 v[104:105], s[90:91], s68, v104, 0
	v_mov_b32_e32 v107, v106
	v_add3_u32 v105, v105, v109, v108
	v_cvt_pk_bf16_f32 v92, v92, v93
	v_cvt_pk_bf16_f32 v93, v94, v95
	v_cvt_pk_bf16_f32 v94, v88, v89
	v_mov_b32_e32 v88, v106
	v_mov_b32_e32 v89, v106
	v_lshl_add_u64 v[104:105], v[104:105], 1, v[162:163]
	v_pk_mul_f32 v[86:87], v[86:87], v[88:89]
	v_pk_mul_f32 v[84:85], v[84:85], v[106:107]
	v_pk_mul_f32 v[82:83], v[82:83], v[88:89]
	s_and_b64 vcc, exec, s[2:3]
	v_pk_mul_f32 v[80:81], v[80:81], v[106:107]
	v_cvt_pk_bf16_f32 v95, v90, v91
	s_cmp_eq_u64 s[0:1], 0
	s_cbranch_scc1 .Lwtp1_4
	global_store_dwordx4 v[104:105], v[92:95], off
	s_branch .Lwtp1d_4
.Lwtp1_4:
	global_store_dwordx4 v[104:105], v[92:95], off sc1
.Lwtp1d_4:
	s_cbranch_vccnz .LBB0_275
	v_pk_mul_f32 v[90:91], v[84:85], v[100:101] op_sel:[1,0] op_sel_hi:[0,0]
	v_pk_fma_f32 v[88:89], v[84:85], v[96:97], v[90:91] op_sel_hi:[1,0,1] neg_lo:[0,0,1] neg_hi:[0,0,1]
	v_pk_fma_f32 v[84:85], v[84:85], v[96:97], v[90:91] op_sel_hi:[1,0,1]
	v_mov_b32_e32 v100, v97
	v_mul_f32_e32 v84, v87, v101
	v_pk_fma_f32 v[90:91], v[86:87], v[100:101], v[84:85] op_sel_hi:[1,1,0] neg_lo:[0,0,1] neg_hi:[0,0,1]
	v_mov_b32_e32 v96, v101
	v_mul_f32_e32 v84, v87, v97
	v_pk_fma_f32 v[86:87], v[86:87], v[96:97], v[84:85] op_sel_hi:[1,1,0]
	v_mov_b32_e32 v89, v85
	v_pk_mul_f32 v[84:85], v[80:81], v[102:103] op_sel:[1,0] op_sel_hi:[0,0]
	v_pk_fma_f32 v[92:93], v[80:81], v[98:99], v[84:85] op_sel_hi:[1,0,1] neg_lo:[0,0,1] neg_hi:[0,0,1]
	v_pk_fma_f32 v[80:81], v[80:81], v[98:99], v[84:85] op_sel_hi:[1,0,1]
	v_mov_b32_e32 v102, v99
	v_mul_f32_e32 v80, v83, v103
	v_pk_fma_f32 v[94:95], v[82:83], v[102:103], v[80:81] op_sel_hi:[1,1,0] neg_lo:[0,0,1] neg_hi:[0,0,1]
	v_mov_b32_e32 v98, v103
	v_mul_f32_e32 v80, v83, v99
	v_pk_fma_f32 v[82:83], v[82:83], v[98:99], v[80:81] op_sel_hi:[1,1,0]
	v_mov_b32_e32 v93, v81
	v_mov_b32_e32 v91, v86
	v_mov_b32_e32 v95, v82
	v_mov_b64_e32 v[84:85], v[88:89]
	v_mov_b64_e32 v[80:81], v[92:93]
	v_mov_b64_e32 v[86:87], v[90:91]
	v_mov_b64_e32 v[82:83], v[94:95]

; __device__ __forceinline__ unsigned cvt_pk_bf16(float lo, float hi) { unsigned r; asm volatile("v_cvt_pk_bf16_f32 %0, %1, %2" : "=v"(r) : "v"(lo), "v"(hi)); return r; }
;     __device__ __forceinline__ void operator()(const f32x4 (&acc)[2][2][4][2], const Unit& u, int wr, int wc, int fr, int fq) const {
;     ...
;                 const int row = row0 + ai * HALF + m * 16; const float rsv = rs[row] * sc;
;                 f32x4 cs = (f32x4){1.f, 1.f, 1.f, 1.f}, sn = (f32x4){0.f, 0.f, 0.f, 0.f};
;                 if (ropel) { const int t = row & 8191; cs = *(const f32x4*)(rope + t * 8 + 4 * fq); sn = *(const f32x4*)(rope + 65536 + t * 8 + 4 * fq); }
;                 bf16_t* rowp = base + (size_t)row * ldc + col0;
; #pragma unroll
;                 for (int bj = 0; bj < 2; ++bj) {
;                     f32x4 v0 = acc[ai][bj][m][0] * rsv, v1 = acc[ai][bj][m][1] * rsv;
;                     if (dorope) {
;                         const f32x4 a0 = v0, a1 = v1;
;                         v0[0] = a0[0] * cs[0] - a0[1] * sn[0]; v0[1] = a0[1] * cs[0] + a0[0] * sn[0];
;                         v0[2] = a0[2] * cs[1] - a0[3] * sn[1]; v0[3] = a0[3] * cs[1] + a0[2] * sn[1];
;                         v1[0] = a1[0] * cs[2] - a1[1] * sn[2]; v1[1] = a1[1] * cs[2] + a1[0] * sn[2];
;                         v1[2] = a1[2] * cs[3] - a1[3] * sn[3]; v1[3] = a1[3] * cs[3] + a1[2] * sn[3];
;                     }
;                     if (dosilu) {
; #pragma unroll
;                         for (int e_ = 0; e_ < 4; ++e_) { v0[e_] = v0[e_] * __builtin_amdgcn_rcpf(1.f + __builtin_amdgcn_exp2f(v0[e_] * -1.4426950408889634f)); v1[e_] = v1[e_] * __builtin_amdgcn_rcpf(1.f + __builtin_amdgcn_exp2f(v1[e_] * -1.4426950408889634f)); }
;                     }
;                     u32x4 w; w.x = cvt_pk_bf16(v0[0], v0[1]); w.y = cvt_pk_bf16(v0[2], v0[3]); w.z = cvt_pk_bf16(v1[0], v1[1]); w.w = cvt_pk_bf16(v1[2], v1[3]);
;                     *(u32x4*)(rowp + bj * HALF) = w;
.LBB0_277:
	v_or_b32_e32 v88, 48, v158
	v_ashrrev_i32_e32 v89, 31, v88
	v_cvt_pk_bf16_f32 v84, v84, v85
	v_cvt_pk_bf16_f32 v85, v86, v87
	v_cvt_pk_bf16_f32 v86, v80, v81
	v_cvt_pk_bf16_f32 v87, v82, v83
	s_cmp_eq_u64 s[0:1], 0
	s_cbranch_scc1 .Lwtp1_5
	global_store_dwordx4 v[104:105], v[84:87], off offset:256
	s_branch .Lwtp1d_5
.Lwtp1_5:
	global_store_dwordx4 v[104:105], v[84:87], off offset:256 sc1
.Lwtp1d_5:
	v_lshl_add_u64 v[80:81], v[88:89], 2, s[6:7]
	v_mov_b32_e32 v90, v233
	v_mov_b32_e32 v84, 0
	v_mov_b32_e32 v80, 1.0
	v_mov_b32_e32 v81, 1.0
	v_mov_b32_e32 v82, 1.0
	v_mov_b32_e32 v83, 1.0
	v_mov_b32_e32 v85, 0
	v_mov_b32_e32 v86, 0
	v_mov_b32_e32 v87, 0
	s_and_saveexec_b64 s[90:91], s[88:89]
	s_cbranch_execz .LBB0_279
	v_lshlrev_b32_e32 v80, 5, v88
	v_and_b32_e32 v144, 0x3ffe0, v80
	v_lshl_add_u64 v[84:85], v[148:149], 0, v[144:145]
	v_lshl_add_u64 v[80:81], v[146:147], 0, v[144:145]
	global_load_dwordx4 v[80:83], v[80:81], off
	s_nop 0
	global_load_dwordx4 v[84:87], v[84:85], off
	s_waitcnt vmcnt(0)

; __device__ __forceinline__ unsigned cvt_pk_bf16(float lo, float hi) { unsigned r; asm volatile("v_cvt_pk_bf16_f32 %0, %1, %2" : "=v"(r) : "v"(lo), "v"(hi)); return r; }
;     __device__ __forceinline__ void operator()(const f32x4 (&acc)[2][2][4][2], const Unit& u, int wr, int wc, int fr, int fq) const {
;     ...
;                 const int row = row0 + ai * HALF + m * 16; const float rsv = rs[row] * sc;
;                 f32x4 cs = (f32x4){1.f, 1.f, 1.f, 1.f}, sn = (f32x4){0.f, 0.f, 0.f, 0.f};
;                 if (ropel) { const int t = row & 8191; cs = *(const f32x4*)(rope + t * 8 + 4 * fq); sn = *(const f32x4*)(rope + 65536 + t * 8 + 4 * fq); }
;                 bf16_t* rowp = base + (size_t)row * ldc + col0;
; #pragma unroll
;                 for (int bj = 0; bj < 2; ++bj) {
;                     f32x4 v0 = acc[ai][bj][m][0] * rsv, v1 = acc[ai][bj][m][1] * rsv;
;                     if (dorope) {
;                         const f32x4 a0 = v0, a1 = v1;
;                         v0[0] = a0[0] * cs[0] - a0[1] * sn[0]; v0[1] = a0[1] * cs[0] + a0[0] * sn[0];
;                         v0[2] = a0[2] * cs[1] - a0[3] * sn[1]; v0[3] = a0[3] * cs[1] + a0[2] * sn[1];
;                         v1[0] = a1[0] * cs[2] - a1[1] * sn[2]; v1[1] = a1[1] * cs[2] + a1[0] * sn[2];
;                         v1[2] = a1[2] * cs[3] - a1[3] * sn[3]; v1[3] = a1[3] * cs[3] + a1[2] * sn[3];
;                     }
;                     if (dosilu) {
; #pragma unroll
;                         for (int e_ = 0; e_ < 4; ++e_) { v0[e_] = v0[e_] * __builtin_amdgcn_rcpf(1.f + __builtin_amdgcn_exp2f(v0[e_] * -1.4426950408889634f)); v1[e_] = v1[e_] * __builtin_amdgcn_rcpf(1.f + __builtin_amdgcn_exp2f(v1[e_] * -1.4426950408889634f)); }
;                     }
;                     u32x4 w; w.x = cvt_pk_bf16(v0[0], v0[1]); w.y = cvt_pk_bf16(v0[2], v0[3]); w.z = cvt_pk_bf16(v1[0], v1[1]); w.w = cvt_pk_bf16(v1[2], v1[3]);
;                     *(u32x4*)(rowp + bj * HALF) = w;
.LBB0_283:
	v_mul_lo_u32 v92, s69, v88
	v_mul_lo_u32 v93, s68, v89
	v_mad_u64_u32 v[88:89], s[90:91], s68, v88, 0
	v_mov_b32_e32 v91, v90
	v_add3_u32 v89, v89, v93, v92
	v_cvt_pk_bf16_f32 v76, v76, v77
	v_cvt_pk_bf16_f32 v77, v78, v79
	v_cvt_pk_bf16_f32 v78, v72, v73
	v_mov_b32_e32 v72, v90
	v_mov_b32_e32 v73, v90
	v_lshl_add_u64 v[88:89], v[88:89], 1, v[162:163]
	v_pk_mul_f32 v[70:71], v[70:71], v[72:73]
	v_pk_mul_f32 v[68:69], v[68:69], v[90:91]
	v_pk_mul_f32 v[66:67], v[66:67], v[72:73]
	s_and_b64 vcc, exec, s[2:3]
	v_pk_mul_f32 v[64:65], v[64:65], v[90:91]
	v_cvt_pk_bf16_f32 v79, v74, v75
	s_cmp_eq_u64 s[0:1], 0
	s_cbranch_scc1 .Lwtp1_6
	global_store_dwordx4 v[88:89], v[76:79], off
	s_branch .Lwtp1d_6
.Lwtp1_6:
	global_store_dwordx4 v[88:89], v[76:79], off sc1
.Lwtp1d_6:
	s_cbranch_vccnz .LBB0_285
	v_pk_mul_f32 v[74:75], v[68:69], v[84:85] op_sel:[1,0] op_sel_hi:[0,0]
	v_pk_fma_f32 v[72:73], v[68:69], v[80:81], v[74:75] op_sel_hi:[1,0,1] neg_lo:[0,0,1] neg_hi:[0,0,1]
	v_pk_fma_f32 v[68:69], v[68:69], v[80:81], v[74:75] op_sel_hi:[1,0,1]
	v_mov_b32_e32 v84, v81
	v_mul_f32_e32 v68, v71, v85
	v_pk_fma_f32 v[74:75], v[70:71], v[84:85], v[68:69] op_sel_hi:[1,1,0] neg_lo:[0,0,1] neg_hi:[0,0,1]
	v_mov_b32_e32 v80, v85
	v_mul_f32_e32 v68, v71, v81
	v_pk_fma_f32 v[70:71], v[70:71], v[80:81], v[68:69] op_sel_hi:[1,1,0]
	v_mov_b32_e32 v73, v69
	v_pk_mul_f32 v[68:69], v[64:65], v[86:87] op_sel:[1,0] op_sel_hi:[0,0]
	v_pk_fma_f32 v[76:77], v[64:65], v[82:83], v[68:69] op_sel_hi:[1,0,1] neg_lo:[0,0,1] neg_hi:[0,0,1]
	v_pk_fma_f32 v[64:65], v[64:65], v[82:83], v[68:69] op_sel_hi:[1,0,1]
	v_mov_b32_e32 v86, v83
	v_mul_f32_e32 v64, v67, v87
	v_pk_fma_f32 v[78:79], v[66:67], v[86:87], v[64:65] op_sel_hi:[1,1,0] neg_lo:[0,0,1] neg_hi:[0,0,1]
	v_mov_b32_e32 v82, v87
	v_mul_f32_e32 v64, v67, v83
	v_pk_fma_f32 v[66:67], v[66:67], v[82:83], v[64:65] op_sel_hi:[1,1,0]
	v_mov_b32_e32 v77, v65
	v_mov_b32_e32 v75, v70
	v_mov_b32_e32 v79, v66
	v_mov_b64_e32 v[68:69], v[72:73]
	v_mov_b64_e32 v[64:65], v[76:77]
	v_mov_b64_e32 v[70:71], v[74:75]
	v_mov_b64_e32 v[66:67], v[78:79]

; __device__ __forceinline__ unsigned cvt_pk_bf16(float lo, float hi) { unsigned r; asm volatile("v_cvt_pk_bf16_f32 %0, %1, %2" : "=v"(r) : "v"(lo), "v"(hi)); return r; }
;     __device__ __forceinline__ void operator()(const f32x4 (&acc)[2][2][4][2], const Unit& u, int wr, int wc, int fr, int fq) const {
;     ...
;                 const int row = row0 + ai * HALF + m * 16; const float rsv = rs[row] * sc;
;                 f32x4 cs = (f32x4){1.f, 1.f, 1.f, 1.f}, sn = (f32x4){0.f, 0.f, 0.f, 0.f};
;                 if (ropel) { const int t = row & 8191; cs = *(const f32x4*)(rope + t * 8 + 4 * fq); sn = *(const f32x4*)(rope + 65536 + t * 8 + 4 * fq); }
;                 bf16_t* rowp = base + (size_t)row * ldc + col0;
; #pragma unroll
;                 for (int bj = 0; bj < 2; ++bj) {
;                     f32x4 v0 = acc[ai][bj][m][0] * rsv, v1 = acc[ai][bj][m][1] * rsv;
;                     if (dorope) {
;                         const f32x4 a0 = v0, a1 = v1;
;                         v0[0] = a0[0] * cs[0] - a0[1] * sn[0]; v0[1] = a0[1] * cs[0] + a0[0] * sn[0];
;                         v0[2] = a0[2] * cs[1] - a0[3] * sn[1]; v0[3] = a0[3] * cs[1] + a0[2] * sn[1];
;                         v1[0] = a1[0] * cs[2] - a1[1] * sn[2]; v1[1] = a1[1] * cs[2] + a1[0] * sn[2];
;                         v1[2] = a1[2] * cs[3] - a1[3] * sn[3]; v1[3] = a1[3] * cs[3] + a1[2] * sn[3];
;                     }
;                     if (dosilu) {
; #pragma unroll
;                         for (int e_ = 0; e_ < 4; ++e_) { v0[e_] = v0[e_] * __builtin_amdgcn_rcpf(1.f + __builtin_amdgcn_exp2f(v0[e_] * -1.4426950408889634f)); v1[e_] = v1[e_] * __builtin_amdgcn_rcpf(1.f + __builtin_amdgcn_exp2f(v1[e_] * -1.4426950408889634f)); }
;                     }
;                     u32x4 w; w.x = cvt_pk_bf16(v0[0], v0[1]); w.y = cvt_pk_bf16(v0[2], v0[3]); w.z = cvt_pk_bf16(v1[0], v1[1]); w.w = cvt_pk_bf16(v1[2], v1[3]);
;                     *(u32x4*)(rowp + bj * HALF) = w;
.LBB0_287:
	v_cvt_pk_bf16_f32 v68, v68, v69
	v_cvt_pk_bf16_f32 v69, v70, v71
	v_cvt_pk_bf16_f32 v70, v64, v65
	s_nop 0
	v_cvt_pk_bf16_f32 v71, v66, v67
	s_cmp_eq_u64 s[0:1], 0
	s_cbranch_scc1 .Lwtp1_7
	global_store_dwordx4 v[88:89], v[68:71], off offset:256
	s_branch .Lwtp1d_7
.Lwtp1_7:
	global_store_dwordx4 v[88:89], v[68:71], off offset:256 sc1
.Lwtp1d_7:
	v_mov_b32_e32 v72, v234
	v_add_u32_e32 v74, 0x80, v158
	v_ashrrev_i32_e32 v75, 31, v74
	v_mov_b32_e32 v68, 0
	v_mov_b32_e32 v64, 1.0
	v_mov_b32_e32 v65, 1.0
	v_mov_b32_e32 v66, 1.0
	v_mov_b32_e32 v67, 1.0
	v_mov_b32_e32 v69, 0
	v_mov_b32_e32 v70, 0
	v_mov_b32_e32 v71, 0
	s_and_saveexec_b64 s[90:91], s[88:89]
	s_cbranch_execz .LBB0_289
	v_lshlrev_b32_e32 v64, 5, v74
	v_and_b32_e32 v144, 0x3f9e0, v64
	v_lshl_add_u64 v[68:69], v[148:149], 0, v[144:145]
	v_lshl_add_u64 v[64:65], v[146:147], 0, v[144:145]
	global_load_dwordx4 v[64:67], v[64:65], off
	s_nop 0
	global_load_dwordx4 v[68:71], v[68:69], off
	s_waitcnt vmcnt(0)

; __device__ __forceinline__ unsigned cvt_pk_bf16(float lo, float hi) { unsigned r; asm volatile("v_cvt_pk_bf16_f32 %0, %1, %2" : "=v"(r) : "v"(lo), "v"(hi)); return r; }
;     __device__ __forceinline__ void operator()(const f32x4 (&acc)[2][2][4][2], const Unit& u, int wr, int wc, int fr, int fq) const {
;     ...
;                 const int row = row0 + ai * HALF + m * 16; const float rsv = rs[row] * sc;
;                 f32x4 cs = (f32x4){1.f, 1.f, 1.f, 1.f}, sn = (f32x4){0.f, 0.f, 0.f, 0.f};
;                 if (ropel) { const int t = row & 8191; cs = *(const f32x4*)(rope + t * 8 + 4 * fq); sn = *(const f32x4*)(rope + 65536 + t * 8 + 4 * fq); }
;                 bf16_t* rowp = base + (size_t)row * ldc + col0;
; #pragma unroll
;                 for (int bj = 0; bj < 2; ++bj) {
;                     f32x4 v0 = acc[ai][bj][m][0] * rsv, v1 = acc[ai][bj][m][1] * rsv;
;                     if (dorope) {
;                         const f32x4 a0 = v0, a1 = v1;
;                         v0[0] = a0[0] * cs[0] - a0[1] * sn[0]; v0[1] = a0[1] * cs[0] + a0[0] * sn[0];
;                         v0[2] = a0[2] * cs[1] - a0[3] * sn[1]; v0[3] = a0[3] * cs[1] + a0[2] * sn[1];
;                         v1[0] = a1[0] * cs[2] - a1[1] * sn[2]; v1[1] = a1[1] * cs[2] + a1[0] * sn[2];
;                         v1[2] = a1[2] * cs[3] - a1[3] * sn[3]; v1[3] = a1[3] * cs[3] + a1[2] * sn[3];
;                     }
;                     if (dosilu) {
; #pragma unroll
;                         for (int e_ = 0; e_ < 4; ++e_) { v0[e_] = v0[e_] * __builtin_amdgcn_rcpf(1.f + __builtin_amdgcn_exp2f(v0[e_] * -1.4426950408889634f)); v1[e_] = v1[e_] * __builtin_amdgcn_rcpf(1.f + __builtin_amdgcn_exp2f(v1[e_] * -1.4426950408889634f)); }
;                     }
;                     u32x4 w; w.x = cvt_pk_bf16(v0[0], v0[1]); w.y = cvt_pk_bf16(v0[2], v0[3]); w.z = cvt_pk_bf16(v1[0], v1[1]); w.w = cvt_pk_bf16(v1[2], v1[3]);
;                     *(u32x4*)(rowp + bj * HALF) = w;
.LBB0_293:
	v_mul_lo_u32 v76, s69, v74
	v_mul_lo_u32 v77, s68, v75
	v_mad_u64_u32 v[74:75], s[90:91], s68, v74, 0
	v_mov_b32_e32 v73, v72
	v_add3_u32 v75, v75, v77, v76
	v_cvt_pk_bf16_f32 v60, v60, v61
	v_cvt_pk_bf16_f32 v61, v62, v63
	v_cvt_pk_bf16_f32 v62, v56, v57
	v_mov_b32_e32 v56, v72
	v_mov_b32_e32 v57, v72
	v_lshl_add_u64 v[74:75], v[74:75], 1, v[162:163]
	v_pk_mul_f32 v[54:55], v[54:55], v[56:57]
	v_pk_mul_f32 v[52:53], v[52:53], v[72:73]
	v_pk_mul_f32 v[50:51], v[50:51], v[56:57]
	s_and_b64 vcc, exec, s[2:3]
	v_pk_mul_f32 v[48:49], v[48:49], v[72:73]
	v_cvt_pk_bf16_f32 v63, v58, v59
	s_cmp_eq_u64 s[0:1], 0
	s_cbranch_scc1 .Lwtp1_8
	global_store_dwordx4 v[74:75], v[60:63], off
	s_branch .Lwtp1d_8
.Lwtp1_8:
	global_store_dwordx4 v[74:75], v[60:63], off sc1
.Lwtp1d_8:
	s_cbranch_vccnz .LBB0_295
	v_pk_mul_f32 v[58:59], v[52:53], v[68:69] op_sel:[1,0] op_sel_hi:[0,0]
	v_pk_fma_f32 v[56:57], v[52:53], v[64:65], v[58:59] op_sel_hi:[1,0,1] neg_lo:[0,0,1] neg_hi:[0,0,1]
	v_pk_fma_f32 v[52:53], v[52:53], v[64:65], v[58:59] op_sel_hi:[1,0,1]
	v_mov_b32_e32 v68, v65
	v_mul_f32_e32 v52, v55, v69
	v_pk_fma_f32 v[58:59], v[54:55], v[68:69], v[52:53] op_sel_hi:[1,1,0] neg_lo:[0,0,1] neg_hi:[0,0,1]
	v_mov_b32_e32 v64, v69
	v_mul_f32_e32 v52, v55, v65
	v_pk_fma_f32 v[54:55], v[54:55], v[64:65], v[52:53] op_sel_hi:[1,1,0]
	v_mov_b32_e32 v57, v53
	v_pk_mul_f32 v[52:53], v[48:49], v[70:71] op_sel:[1,0] op_sel_hi:[0,0]
	v_pk_fma_f32 v[60:61], v[48:49], v[66:67], v[52:53] op_sel_hi:[1,0,1] neg_lo:[0,0,1] neg_hi:[0,0,1]
	v_pk_fma_f32 v[48:49], v[48:49], v[66:67], v[52:53] op_sel_hi:[1,0,1]
	v_mov_b32_e32 v70, v67
	v_mul_f32_e32 v48, v51, v71
	v_pk_fma_f32 v[62:63], v[50:51], v[70:71], v[48:49] op_sel_hi:[1,1,0] neg_lo:[0,0,1] neg_hi:[0,0,1]
	v_mov_b32_e32 v66, v71
	v_mul_f32_e32 v48, v51, v67
	v_pk_fma_f32 v[50:51], v[50:51], v[66:67], v[48:49] op_sel_hi:[1,1,0]
	v_mov_b32_e32 v61, v49
	v_mov_b32_e32 v59, v54
	v_mov_b32_e32 v63, v50
	v_mov_b64_e32 v[52:53], v[56:57]
	v_mov_b64_e32 v[48:49], v[60:61]
	v_mov_b64_e32 v[54:55], v[58:59]
	v_mov_b64_e32 v[50:51], v[62:63]

; __device__ __forceinline__ unsigned cvt_pk_bf16(float lo, float hi) { unsigned r; asm volatile("v_cvt_pk_bf16_f32 %0, %1, %2" : "=v"(r) : "v"(lo), "v"(hi)); return r; }
;     __device__ __forceinline__ void operator()(const f32x4 (&acc)[2][2][4][2], const Unit& u, int wr, int wc, int fr, int fq) const {
;     ...
;                 const int row = row0 + ai * HALF + m * 16; const float rsv = rs[row] * sc;
;                 f32x4 cs = (f32x4){1.f, 1.f, 1.f, 1.f}, sn = (f32x4){0.f, 0.f, 0.f, 0.f};
;                 if (ropel) { const int t = row & 8191; cs = *(const f32x4*)(rope + t * 8 + 4 * fq); sn = *(const f32x4*)(rope + 65536 + t * 8 + 4 * fq); }
;                 bf16_t* rowp = base + (size_t)row * ldc + col0;
; #pragma unroll
;                 for (int bj = 0; bj < 2; ++bj) {
;                     f32x4 v0 = acc[ai][bj][m][0] * rsv, v1 = acc[ai][bj][m][1] * rsv;
;                     if (dorope) {
;                         const f32x4 a0 = v0, a1 = v1;
;                         v0[0] = a0[0] * cs[0] - a0[1] * sn[0]; v0[1] = a0[1] * cs[0] + a0[0] * sn[0];
;                         v0[2] = a0[2] * cs[1] - a0[3] * sn[1]; v0[3] = a0[3] * cs[1] + a0[2] * sn[1];
;                         v1[0] = a1[0] * cs[2] - a1[1] * sn[2]; v1[1] = a1[1] * cs[2] + a1[0] * sn[2];
;                         v1[2] = a1[2] * cs[3] - a1[3] * sn[3]; v1[3] = a1[3] * cs[3] + a1[2] * sn[3];
;                     }
;                     if (dosilu) {
; #pragma unroll
;                         for (int e_ = 0; e_ < 4; ++e_) { v0[e_] = v0[e_] * __builtin_amdgcn_rcpf(1.f + __builtin_amdgcn_exp2f(v0[e_] * -1.4426950408889634f)); v1[e_] = v1[e_] * __builtin_amdgcn_rcpf(1.f + __builtin_amdgcn_exp2f(v1[e_] * -1.4426950408889634f)); }
;                     }
;                     u32x4 w; w.x = cvt_pk_bf16(v0[0], v0[1]); w.y = cvt_pk_bf16(v0[2], v0[3]); w.z = cvt_pk_bf16(v1[0], v1[1]); w.w = cvt_pk_bf16(v1[2], v1[3]);
;                     *(u32x4*)(rowp + bj * HALF) = w;
.LBB0_297:
	v_cvt_pk_bf16_f32 v52, v52, v53
	v_cvt_pk_bf16_f32 v53, v54, v55
	v_cvt_pk_bf16_f32 v54, v48, v49
	s_nop 0
	v_cvt_pk_bf16_f32 v55, v50, v51
	s_cmp_eq_u64 s[0:1], 0
	s_cbranch_scc1 .Lwtp1_9
	global_store_dwordx4 v[74:75], v[52:55], off offset:256
	s_branch .Lwtp1d_9
.Lwtp1_9:
	global_store_dwordx4 v[74:75], v[52:55], off offset:256 sc1
.Lwtp1d_9:
	v_mov_b32_e32 v56, v235
	v_add_u32_e32 v58, 0x90, v158
	v_ashrrev_i32_e32 v59, 31, v58
	v_mov_b32_e32 v52, 0
	v_mov_b32_e32 v48, 1.0
	v_mov_b32_e32 v49, 1.0
	v_mov_b32_e32 v50, 1.0
	v_mov_b32_e32 v51, 1.0
	v_mov_b32_e32 v53, 0
	v_mov_b32_e32 v54, 0
	v_mov_b32_e32 v55, 0
	s_and_saveexec_b64 s[90:91], s[88:89]
	s_cbranch_execz .LBB0_299
	v_lshlrev_b32_e32 v48, 5, v58
	v_and_b32_e32 v144, 0x3fbe0, v48
	v_lshl_add_u64 v[52:53], v[148:149], 0, v[144:145]
	v_lshl_add_u64 v[48:49], v[146:147], 0, v[144:145]
	global_load_dwordx4 v[48:51], v[48:49], off
	s_nop 0
	global_load_dwordx4 v[52:55], v[52:53], off
	s_waitcnt vmcnt(0)

; __device__ __forceinline__ unsigned cvt_pk_bf16(float lo, float hi) { unsigned r; asm volatile("v_cvt_pk_bf16_f32 %0, %1, %2" : "=v"(r) : "v"(lo), "v"(hi)); return r; }
;     __device__ __forceinline__ void operator()(const f32x4 (&acc)[2][2][4][2], const Unit& u, int wr, int wc, int fr, int fq) const {
;     ...
;                 const int row = row0 + ai * HALF + m * 16; const float rsv = rs[row] * sc;
;                 f32x4 cs = (f32x4){1.f, 1.f, 1.f, 1.f}, sn = (f32x4){0.f, 0.f, 0.f, 0.f};
;                 if (ropel) { const int t = row & 8191; cs = *(const f32x4*)(rope + t * 8 + 4 * fq); sn = *(const f32x4*)(rope + 65536 + t * 8 + 4 * fq); }
;                 bf16_t* rowp = base + (size_t)row * ldc + col0;
; #pragma unroll
;                 for (int bj = 0; bj < 2; ++bj) {
;                     f32x4 v0 = acc[ai][bj][m][0] * rsv, v1 = acc[ai][bj][m][1] * rsv;
;                     if (dorope) {
;                         const f32x4 a0 = v0, a1 = v1;
;                         v0[0] = a0[0] * cs[0] - a0[1] * sn[0]; v0[1] = a0[1] * cs[0] + a0[0] * sn[0];
;                         v0[2] = a0[2] * cs[1] - a0[3] * sn[1]; v0[3] = a0[3] * cs[1] + a0[2] * sn[1];
;                         v1[0] = a1[0] * cs[2] - a1[1] * sn[2]; v1[1] = a1[1] * cs[2] + a1[0] * sn[2];
;                         v1[2] = a1[2] * cs[3] - a1[3] * sn[3]; v1[3] = a1[3] * cs[3] + a1[2] * sn[3];
;                     }
;                     if (dosilu) {
; #pragma unroll
;                         for (int e_ = 0; e_ < 4; ++e_) { v0[e_] = v0[e_] * __builtin_amdgcn_rcpf(1.f + __builtin_amdgcn_exp2f(v0[e_] * -1.4426950408889634f)); v1[e_] = v1[e_] * __builtin_amdgcn_rcpf(1.f + __builtin_amdgcn_exp2f(v1[e_] * -1.4426950408889634f)); }
;                     }
;                     u32x4 w; w.x = cvt_pk_bf16(v0[0], v0[1]); w.y = cvt_pk_bf16(v0[2], v0[3]); w.z = cvt_pk_bf16(v1[0], v1[1]); w.w = cvt_pk_bf16(v1[2], v1[3]);
;                     *(u32x4*)(rowp + bj * HALF) = w;
.LBB0_303:
	v_mul_lo_u32 v60, s69, v58
	v_mul_lo_u32 v61, s68, v59
	v_mad_u64_u32 v[58:59], s[90:91], s68, v58, 0
	v_mov_b32_e32 v57, v56
	v_add3_u32 v59, v59, v61, v60
	v_cvt_pk_bf16_f32 v44, v44, v45
	v_cvt_pk_bf16_f32 v45, v46, v47
	v_cvt_pk_bf16_f32 v46, v40, v41
	v_mov_b32_e32 v40, v56
	v_mov_b32_e32 v41, v56
	v_lshl_add_u64 v[58:59], v[58:59], 1, v[162:163]
	v_pk_mul_f32 v[38:39], v[38:39], v[40:41]
	v_pk_mul_f32 v[36:37], v[36:37], v[56:57]
	v_pk_mul_f32 v[34:35], v[34:35], v[40:41]
	s_and_b64 vcc, exec, s[2:3]
	v_pk_mul_f32 v[32:33], v[32:33], v[56:57]
	v_cvt_pk_bf16_f32 v47, v42, v43
	s_cmp_eq_u64 s[0:1], 0
	s_cbranch_scc1 .Lwtp1_10
	global_store_dwordx4 v[58:59], v[44:47], off
	s_branch .Lwtp1d_10
.Lwtp1_10:
	global_store_dwordx4 v[58:59], v[44:47], off sc1
.Lwtp1d_10:
	s_cbranch_vccnz .LBB0_305
	v_pk_mul_f32 v[42:43], v[36:37], v[52:53] op_sel:[1,0] op_sel_hi:[0,0]
	v_pk_fma_f32 v[40:41], v[36:37], v[48:49], v[42:43] op_sel_hi:[1,0,1] neg_lo:[0,0,1] neg_hi:[0,0,1]
	v_pk_fma_f32 v[36:37], v[36:37], v[48:49], v[42:43] op_sel_hi:[1,0,1]
	v_mov_b32_e32 v52, v49
	v_mul_f32_e32 v36, v39, v53
	v_pk_fma_f32 v[42:43], v[38:39], v[52:53], v[36:37] op_sel_hi:[1,1,0] neg_lo:[0,0,1] neg_hi:[0,0,1]
	v_mov_b32_e32 v48, v53
	v_mul_f32_e32 v36, v39, v49
	v_pk_fma_f32 v[38:39], v[38:39], v[48:49], v[36:37] op_sel_hi:[1,1,0]
	v_mov_b32_e32 v41, v37
	v_pk_mul_f32 v[36:37], v[32:33], v[54:55] op_sel:[1,0] op_sel_hi:[0,0]
	v_pk_fma_f32 v[44:45], v[32:33], v[50:51], v[36:37] op_sel_hi:[1,0,1] neg_lo:[0,0,1] neg_hi:[0,0,1]
	v_pk_fma_f32 v[32:33], v[32:33], v[50:51], v[36:37] op_sel_hi:[1,0,1]
	v_mov_b32_e32 v54, v51
	v_mul_f32_e32 v32, v35, v55
	v_pk_fma_f32 v[46:47], v[34:35], v[54:55], v[32:33] op_sel_hi:[1,1,0] neg_lo:[0,0,1] neg_hi:[0,0,1]
	v_mov_b32_e32 v50, v55
	v_mul_f32_e32 v32, v35, v51
	v_pk_fma_f32 v[34:35], v[34:35], v[50:51], v[32:33] op_sel_hi:[1,1,0]
	v_mov_b32_e32 v45, v33
	v_mov_b32_e32 v43, v38
	v_mov_b32_e32 v47, v34
	v_mov_b64_e32 v[36:37], v[40:41]
	v_mov_b64_e32 v[32:33], v[44:45]
	v_mov_b64_e32 v[38:39], v[42:43]
	v_mov_b64_e32 v[34:35], v[46:47]

; __device__ __forceinline__ unsigned cvt_pk_bf16(float lo, float hi) { unsigned r; asm volatile("v_cvt_pk_bf16_f32 %0, %1, %2" : "=v"(r) : "v"(lo), "v"(hi)); return r; }
;     __device__ __forceinline__ void operator()(const f32x4 (&acc)[2][2][4][2], const Unit& u, int wr, int wc, int fr, int fq) const {
;     ...
;                 const int row = row0 + ai * HALF + m * 16; const float rsv = rs[row] * sc;
;                 f32x4 cs = (f32x4){1.f, 1.f, 1.f, 1.f}, sn = (f32x4){0.f, 0.f, 0.f, 0.f};
;                 if (ropel) { const int t = row & 8191; cs = *(const f32x4*)(rope + t * 8 + 4 * fq); sn = *(const f32x4*)(rope + 65536 + t * 8 + 4 * fq); }
;                 bf16_t* rowp = base + (size_t)row * ldc + col0;
; #pragma unroll
;                 for (int bj = 0; bj < 2; ++bj) {
;                     f32x4 v0 = acc[ai][bj][m][0] * rsv, v1 = acc[ai][bj][m][1] * rsv;
;                     if (dorope) {
;                         const f32x4 a0 = v0, a1 = v1;
;                         v0[0] = a0[0] * cs[0] - a0[1] * sn[0]; v0[1] = a0[1] * cs[0] + a0[0] * sn[0];
;                         v0[2] = a0[2] * cs[1] - a0[3] * sn[1]; v0[3] = a0[3] * cs[1] + a0[2] * sn[1];
;                         v1[0] = a1[0] * cs[2] - a1[1] * sn[2]; v1[1] = a1[1] * cs[2] + a1[0] * sn[2];
;                         v1[2] = a1[2] * cs[3] - a1[3] * sn[3]; v1[3] = a1[3] * cs[3] + a1[2] * sn[3];
;                     }
;                     if (dosilu) {
; #pragma unroll
;                         for (int e_ = 0; e_ < 4; ++e_) { v0[e_] = v0[e_] * __builtin_amdgcn_rcpf(1.f + __builtin_amdgcn_exp2f(v0[e_] * -1.4426950408889634f)); v1[e_] = v1[e_] * __builtin_amdgcn_rcpf(1.f + __builtin_amdgcn_exp2f(v1[e_] * -1.4426950408889634f)); }
;                     }
;                     u32x4 w; w.x = cvt_pk_bf16(v0[0], v0[1]); w.y = cvt_pk_bf16(v0[2], v0[3]); w.z = cvt_pk_bf16(v1[0], v1[1]); w.w = cvt_pk_bf16(v1[2], v1[3]);
;                     *(u32x4*)(rowp + bj * HALF) = w;
.LBB0_307:
	v_cvt_pk_bf16_f32 v36, v36, v37
	v_cvt_pk_bf16_f32 v37, v38, v39
	v_cvt_pk_bf16_f32 v38, v32, v33
	s_nop 0
	v_cvt_pk_bf16_f32 v39, v34, v35
	s_cmp_eq_u64 s[0:1], 0
	s_cbranch_scc1 .Lwtp1_11
	global_store_dwordx4 v[58:59], v[36:39], off offset:256
	s_branch .Lwtp1d_11
.Lwtp1_11:
	global_store_dwordx4 v[58:59], v[36:39], off offset:256 sc1
.Lwtp1d_11:
	v_mov_b32_e32 v40, v236
	v_add_u32_e32 v42, 0xa0, v158
	v_ashrrev_i32_e32 v43, 31, v42
	v_mov_b32_e32 v36, 0
	v_mov_b32_e32 v32, 1.0
	v_mov_b32_e32 v33, 1.0
	v_mov_b32_e32 v34, 1.0
	v_mov_b32_e32 v35, 1.0
	v_mov_b32_e32 v37, 0
	v_mov_b32_e32 v38, 0
	v_mov_b32_e32 v39, 0
	s_and_saveexec_b64 s[90:91], s[88:89]
	s_cbranch_execz .LBB0_309
	v_lshlrev_b32_e32 v32, 5, v42
	v_and_b32_e32 v144, 0x3fde0, v32
	v_lshl_add_u64 v[36:37], v[148:149], 0, v[144:145]
	v_lshl_add_u64 v[32:33], v[146:147], 0, v[144:145]
	global_load_dwordx4 v[32:35], v[32:33], off
	s_nop 0
	global_load_dwordx4 v[36:39], v[36:37], off
	s_waitcnt vmcnt(0)

; __device__ __forceinline__ unsigned cvt_pk_bf16(float lo, float hi) { unsigned r; asm volatile("v_cvt_pk_bf16_f32 %0, %1, %2" : "=v"(r) : "v"(lo), "v"(hi)); return r; }
;     __device__ __forceinline__ void operator()(const f32x4 (&acc)[2][2][4][2], const Unit& u, int wr, int wc, int fr, int fq) const {
;     ...
;                 const int row = row0 + ai * HALF + m * 16; const float rsv = rs[row] * sc;
;                 f32x4 cs = (f32x4){1.f, 1.f, 1.f, 1.f}, sn = (f32x4){0.f, 0.f, 0.f, 0.f};
;                 if (ropel) { const int t = row & 8191; cs = *(const f32x4*)(rope + t * 8 + 4 * fq); sn = *(const f32x4*)(rope + 65536 + t * 8 + 4 * fq); }
;                 bf16_t* rowp = base + (size_t)row * ldc + col0;
; #pragma unroll
;                 for (int bj = 0; bj < 2; ++bj) {
;                     f32x4 v0 = acc[ai][bj][m][0] * rsv, v1 = acc[ai][bj][m][1] * rsv;
;                     if (dorope) {
;                         const f32x4 a0 = v0, a1 = v1;
;                         v0[0] = a0[0] * cs[0] - a0[1] * sn[0]; v0[1] = a0[1] * cs[0] + a0[0] * sn[0];
;                         v0[2] = a0[2] * cs[1] - a0[3] * sn[1]; v0[3] = a0[3] * cs[1] + a0[2] * sn[1];
;                         v1[0] = a1[0] * cs[2] - a1[1] * sn[2]; v1[1] = a1[1] * cs[2] + a1[0] * sn[2];
;                         v1[2] = a1[2] * cs[3] - a1[3] * sn[3]; v1[3] = a1[3] * cs[3] + a1[2] * sn[3];
;                     }
;                     if (dosilu) {
; #pragma unroll
;                         for (int e_ = 0; e_ < 4; ++e_) { v0[e_] = v0[e_] * __builtin_amdgcn_rcpf(1.f + __builtin_amdgcn_exp2f(v0[e_] * -1.4426950408889634f)); v1[e_] = v1[e_] * __builtin_amdgcn_rcpf(1.f + __builtin_amdgcn_exp2f(v1[e_] * -1.4426950408889634f)); }
;                     }
;                     u32x4 w; w.x = cvt_pk_bf16(v0[0], v0[1]); w.y = cvt_pk_bf16(v0[2], v0[3]); w.z = cvt_pk_bf16(v1[0], v1[1]); w.w = cvt_pk_bf16(v1[2], v1[3]);
;                     *(u32x4*)(rowp + bj * HALF) = w;
.LBB0_313:
	v_mul_lo_u32 v44, s69, v42
	v_mul_lo_u32 v45, s68, v43
	v_mad_u64_u32 v[42:43], s[90:91], s68, v42, 0
	v_mov_b32_e32 v41, v40
	v_add3_u32 v43, v43, v45, v44
	v_cvt_pk_bf16_f32 v28, v28, v29
	v_cvt_pk_bf16_f32 v29, v30, v31
	v_cvt_pk_bf16_f32 v30, v24, v25
	v_mov_b32_e32 v24, v40
	v_mov_b32_e32 v25, v40
	v_lshl_add_u64 v[42:43], v[42:43], 1, v[162:163]
	v_pk_mul_f32 v[22:23], v[22:23], v[24:25]
	v_pk_mul_f32 v[20:21], v[20:21], v[40:41]
	v_pk_mul_f32 v[18:19], v[18:19], v[24:25]
	s_and_b64 vcc, exec, s[2:3]
	v_pk_mul_f32 v[16:17], v[16:17], v[40:41]
	v_cvt_pk_bf16_f32 v31, v26, v27
	s_cmp_eq_u64 s[0:1], 0
	s_cbranch_scc1 .Lwtp1_12
	global_store_dwordx4 v[42:43], v[28:31], off
	s_branch .Lwtp1d_12
.Lwtp1_12:
	global_store_dwordx4 v[42:43], v[28:31], off sc1
.Lwtp1d_12:
	s_cbranch_vccnz .LBB0_315
	v_pk_mul_f32 v[26:27], v[20:21], v[36:37] op_sel:[1,0] op_sel_hi:[0,0]
	v_pk_fma_f32 v[24:25], v[20:21], v[32:33], v[26:27] op_sel_hi:[1,0,1] neg_lo:[0,0,1] neg_hi:[0,0,1]
	v_pk_fma_f32 v[20:21], v[20:21], v[32:33], v[26:27] op_sel_hi:[1,0,1]
	v_mov_b32_e32 v36, v33
	v_mul_f32_e32 v20, v23, v37
	v_pk_fma_f32 v[26:27], v[22:23], v[36:37], v[20:21] op_sel_hi:[1,1,0] neg_lo:[0,0,1] neg_hi:[0,0,1]
	v_mov_b32_e32 v32, v37
	v_mul_f32_e32 v20, v23, v33
	v_pk_fma_f32 v[22:23], v[22:23], v[32:33], v[20:21] op_sel_hi:[1,1,0]
	v_mov_b32_e32 v25, v21
	v_pk_mul_f32 v[20:21], v[16:17], v[38:39] op_sel:[1,0] op_sel_hi:[0,0]
	v_pk_fma_f32 v[28:29], v[16:17], v[34:35], v[20:21] op_sel_hi:[1,0,1] neg_lo:[0,0,1] neg_hi:[0,0,1]
	v_pk_fma_f32 v[16:17], v[16:17], v[34:35], v[20:21] op_sel_hi:[1,0,1]
	v_mov_b32_e32 v38, v35
	v_mul_f32_e32 v16, v19, v39
	v_pk_fma_f32 v[30:31], v[18:19], v[38:39], v[16:17] op_sel_hi:[1,1,0] neg_lo:[0,0,1] neg_hi:[0,0,1]
	v_mov_b32_e32 v34, v39
	v_mul_f32_e32 v16, v19, v35
	v_pk_fma_f32 v[18:19], v[18:19], v[34:35], v[16:17] op_sel_hi:[1,1,0]
	v_mov_b32_e32 v29, v17
	v_mov_b32_e32 v27, v22
	v_mov_b32_e32 v31, v18
	v_mov_b64_e32 v[20:21], v[24:25]
	v_mov_b64_e32 v[16:17], v[28:29]
	v_mov_b64_e32 v[22:23], v[26:27]
	v_mov_b64_e32 v[18:19], v[30:31]

; __device__ __forceinline__ unsigned cvt_pk_bf16(float lo, float hi) { unsigned r; asm volatile("v_cvt_pk_bf16_f32 %0, %1, %2" : "=v"(r) : "v"(lo), "v"(hi)); return r; }
;     __device__ __forceinline__ void operator()(const f32x4 (&acc)[2][2][4][2], const Unit& u, int wr, int wc, int fr, int fq) const {
;     ...
;                 const int row = row0 + ai * HALF + m * 16; const float rsv = rs[row] * sc;
;                 f32x4 cs = (f32x4){1.f, 1.f, 1.f, 1.f}, sn = (f32x4){0.f, 0.f, 0.f, 0.f};
;                 if (ropel) { const int t = row & 8191; cs = *(const f32x4*)(rope + t * 8 + 4 * fq); sn = *(const f32x4*)(rope + 65536 + t * 8 + 4 * fq); }
;                 bf16_t* rowp = base + (size_t)row * ldc + col0;
; #pragma unroll
;                 for (int bj = 0; bj < 2; ++bj) {
;                     f32x4 v0 = acc[ai][bj][m][0] * rsv, v1 = acc[ai][bj][m][1] * rsv;
;                     if (dorope) {
;                         const f32x4 a0 = v0, a1 = v1;
;                         v0[0] = a0[0] * cs[0] - a0[1] * sn[0]; v0[1] = a0[1] * cs[0] + a0[0] * sn[0];
;                         v0[2] = a0[2] * cs[1] - a0[3] * sn[1]; v0[3] = a0[3] * cs[1] + a0[2] * sn[1];
;                         v1[0] = a1[0] * cs[2] - a1[1] * sn[2]; v1[1] = a1[1] * cs[2] + a1[0] * sn[2];
;                         v1[2] = a1[2] * cs[3] - a1[3] * sn[3]; v1[3] = a1[3] * cs[3] + a1[2] * sn[3];
;                     }
;                     if (dosilu) {
; #pragma unroll
;                         for (int e_ = 0; e_ < 4; ++e_) { v0[e_] = v0[e_] * __builtin_amdgcn_rcpf(1.f + __builtin_amdgcn_exp2f(v0[e_] * -1.4426950408889634f)); v1[e_] = v1[e_] * __builtin_amdgcn_rcpf(1.f + __builtin_amdgcn_exp2f(v1[e_] * -1.4426950408889634f)); }
;                     }
;                     u32x4 w; w.x = cvt_pk_bf16(v0[0], v0[1]); w.y = cvt_pk_bf16(v0[2], v0[3]); w.z = cvt_pk_bf16(v1[0], v1[1]); w.w = cvt_pk_bf16(v1[2], v1[3]);
;                     *(u32x4*)(rowp + bj * HALF) = w;
.LBB0_317:
	v_cvt_pk_bf16_f32 v20, v20, v21
	v_cvt_pk_bf16_f32 v21, v22, v23
	v_cvt_pk_bf16_f32 v22, v16, v17
	s_nop 0
	v_cvt_pk_bf16_f32 v23, v18, v19
	s_cmp_eq_u64 s[0:1], 0
	s_cbranch_scc1 .Lwtp1_13
	global_store_dwordx4 v[42:43], v[20:23], off offset:256
	s_branch .Lwtp1d_13
.Lwtp1_13:
	global_store_dwordx4 v[42:43], v[20:23], off offset:256 sc1
.Lwtp1d_13:
	v_mov_b32_e32 v24, v237
	v_add_u32_e32 v26, 0xb0, v158
	v_ashrrev_i32_e32 v27, 31, v26
	v_mov_b32_e32 v20, 0
	v_mov_b32_e32 v16, 1.0
	v_mov_b32_e32 v17, 1.0
	v_mov_b32_e32 v18, 1.0
	v_mov_b32_e32 v19, 1.0
	v_mov_b32_e32 v21, 0
	v_mov_b32_e32 v22, 0
	v_mov_b32_e32 v23, 0
	s_and_saveexec_b64 s[90:91], s[88:89]
	s_cbranch_execz .LBB0_319
	v_lshlrev_b32_e32 v16, 5, v26
	v_and_b32_e32 v144, 0x3ffe0, v16
	v_lshl_add_u64 v[20:21], v[148:149], 0, v[144:145]
	v_lshl_add_u64 v[16:17], v[146:147], 0, v[144:145]
	global_load_dwordx4 v[16:19], v[16:17], off
	s_nop 0
	global_load_dwordx4 v[20:23], v[20:21], off
	s_waitcnt vmcnt(0)

; __device__ __forceinline__ unsigned cvt_pk_bf16(float lo, float hi) { unsigned r; asm volatile("v_cvt_pk_bf16_f32 %0, %1, %2" : "=v"(r) : "v"(lo), "v"(hi)); return r; }
;     __device__ __forceinline__ void operator()(const f32x4 (&acc)[2][2][4][2], const Unit& u, int wr, int wc, int fr, int fq) const {
;     ...
;                 const int row = row0 + ai * HALF + m * 16; const float rsv = rs[row] * sc;
;                 f32x4 cs = (f32x4){1.f, 1.f, 1.f, 1.f}, sn = (f32x4){0.f, 0.f, 0.f, 0.f};
;                 if (ropel) { const int t = row & 8191; cs = *(const f32x4*)(rope + t * 8 + 4 * fq); sn = *(const f32x4*)(rope + 65536 + t * 8 + 4 * fq); }
;                 bf16_t* rowp = base + (size_t)row * ldc + col0;
; #pragma unroll
;                 for (int bj = 0; bj < 2; ++bj) {
;                     f32x4 v0 = acc[ai][bj][m][0] * rsv, v1 = acc[ai][bj][m][1] * rsv;
;                     if (dorope) {
;                         const f32x4 a0 = v0, a1 = v1;
;                         v0[0] = a0[0] * cs[0] - a0[1] * sn[0]; v0[1] = a0[1] * cs[0] + a0[0] * sn[0];
;                         v0[2] = a0[2] * cs[1] - a0[3] * sn[1]; v0[3] = a0[3] * cs[1] + a0[2] * sn[1];
;                         v1[0] = a1[0] * cs[2] - a1[1] * sn[2]; v1[1] = a1[1] * cs[2] + a1[0] * sn[2];
;                         v1[2] = a1[2] * cs[3] - a1[3] * sn[3]; v1[3] = a1[3] * cs[3] + a1[2] * sn[3];
;                     }
;                     if (dosilu) {
; #pragma unroll
;                         for (int e_ = 0; e_ < 4; ++e_) { v0[e_] = v0[e_] * __builtin_amdgcn_rcpf(1.f + __builtin_amdgcn_exp2f(v0[e_] * -1.4426950408889634f)); v1[e_] = v1[e_] * __builtin_amdgcn_rcpf(1.f + __builtin_amdgcn_exp2f(v1[e_] * -1.4426950408889634f)); }
;                     }
;                     u32x4 w; w.x = cvt_pk_bf16(v0[0], v0[1]); w.y = cvt_pk_bf16(v0[2], v0[3]); w.z = cvt_pk_bf16(v1[0], v1[1]); w.w = cvt_pk_bf16(v1[2], v1[3]);
;                     *(u32x4*)(rowp + bj * HALF) = w;
.LBB0_323:
	v_mul_lo_u32 v28, s69, v26
	v_mul_lo_u32 v29, s68, v27
	v_mad_u64_u32 v[26:27], s[68:69], s68, v26, 0
	v_mov_b32_e32 v25, v24
	v_add3_u32 v27, v27, v29, v28
	v_cvt_pk_bf16_f32 v12, v12, v13
	v_cvt_pk_bf16_f32 v13, v14, v15
	v_cvt_pk_bf16_f32 v14, v8, v9
	v_mov_b32_e32 v8, v24
	v_mov_b32_e32 v9, v24
	v_lshl_add_u64 v[26:27], v[26:27], 1, v[162:163]
	v_pk_mul_f32 v[6:7], v[6:7], v[8:9]
	v_pk_mul_f32 v[4:5], v[4:5], v[24:25]
	v_pk_mul_f32 v[2:3], v[2:3], v[8:9]
	s_and_b64 vcc, exec, s[2:3]
	v_pk_mul_f32 v[0:1], v[0:1], v[24:25]
	v_cvt_pk_bf16_f32 v15, v10, v11
	s_cmp_eq_u64 s[0:1], 0
	s_cbranch_scc1 .Lwtp1_14
	global_store_dwordx4 v[26:27], v[12:15], off
	s_branch .Lwtp1d_14
.Lwtp1_14:
	global_store_dwordx4 v[26:27], v[12:15], off sc1
.Lwtp1d_14:
	s_cbranch_vccnz .LBB0_325
	v_pk_mul_f32 v[10:11], v[4:5], v[20:21] op_sel:[1,0] op_sel_hi:[0,0]
	v_pk_fma_f32 v[8:9], v[4:5], v[16:17], v[10:11] op_sel_hi:[1,0,1] neg_lo:[0,0,1] neg_hi:[0,0,1]
	v_pk_fma_f32 v[4:5], v[4:5], v[16:17], v[10:11] op_sel_hi:[1,0,1]
	v_mov_b32_e32 v20, v17
	v_mul_f32_e32 v4, v7, v21
	v_pk_fma_f32 v[10:11], v[6:7], v[20:21], v[4:5] op_sel_hi:[1,1,0] neg_lo:[0,0,1] neg_hi:[0,0,1]
	v_mov_b32_e32 v16, v21
	v_mul_f32_e32 v4, v7, v17
	v_pk_fma_f32 v[6:7], v[6:7], v[16:17], v[4:5] op_sel_hi:[1,1,0]
	v_mov_b32_e32 v9, v5
	v_pk_mul_f32 v[4:5], v[0:1], v[22:23] op_sel:[1,0] op_sel_hi:[0,0]
	v_pk_fma_f32 v[12:13], v[0:1], v[18:19], v[4:5] op_sel_hi:[1,0,1] neg_lo:[0,0,1] neg_hi:[0,0,1]
	v_pk_fma_f32 v[0:1], v[0:1], v[18:19], v[4:5] op_sel_hi:[1,0,1]
	v_mov_b32_e32 v22, v19
	v_mul_f32_e32 v0, v3, v23
	v_pk_fma_f32 v[14:15], v[2:3], v[22:23], v[0:1] op_sel_hi:[1,1,0] neg_lo:[0,0,1] neg_hi:[0,0,1]
	v_mov_b32_e32 v18, v23
	v_mul_f32_e32 v0, v3, v19
	v_pk_fma_f32 v[2:3], v[2:3], v[18:19], v[0:1] op_sel_hi:[1,1,0]
	v_mov_b32_e32 v13, v1
	v_mov_b32_e32 v11, v6
	v_mov_b32_e32 v15, v2
	v_mov_b64_e32 v[4:5], v[8:9]
	v_mov_b64_e32 v[0:1], v[12:13]
	v_mov_b64_e32 v[6:7], v[10:11]
	v_mov_b64_e32 v[2:3], v[14:15]

; __device__ __forceinline__ unsigned cvt_pk_bf16(float lo, float hi) { unsigned r; asm volatile("v_cvt_pk_bf16_f32 %0, %1, %2" : "=v"(r) : "v"(lo), "v"(hi)); return r; }
;     __device__ __forceinline__ void operator()(const f32x4 (&acc)[2][2][4][2], const Unit& u, int wr, int wc, int fr, int fq) const {
;     ...
;                     u32x4 w; w.x = cvt_pk_bf16(v0[0], v0[1]); w.y = cvt_pk_bf16(v0[2], v0[3]); w.z = cvt_pk_bf16(v1[0], v1[1]); w.w = cvt_pk_bf16(v1[2], v1[3]);
;                     *(u32x4*)(rowp + bj * HALF) = w;
; template <class Epi, class Sched, bool ALIGN_EPI = false, bool SP2 = false>
; __device__ __forceinline__ void gemm_phase(PG8_LAS unsigned char* lds, const Gemm g, const Sched& S, const Epi& E, int wid_in) {
;     ...
;         if constexpr (!Epi::AFTER_DRAIN) { E(acc, cur, wr, wc, fr, fq); S.done(cur); }
;         if (!has_next) break;
.LBB0_327:
	s_andn2_b64 vcc, exec, s[0:1]
	s_mov_b64 s[0:1], -1
	v_cvt_pk_bf16_f32 v4, v4, v5
	v_cvt_pk_bf16_f32 v5, v6, v7
	v_cvt_pk_bf16_f32 v6, v0, v1
	v_cvt_pk_bf16_f32 v7, v2, v3
	s_cmp_eq_u64 s[0:1], 0
	s_cbranch_scc1 .Lwtp1_15
	global_store_dwordx4 v[26:27], v[4:7], off offset:256
	s_branch .Lwtp1d_15
.Lwtp1_15:
	global_store_dwordx4 v[26:27], v[4:7], off offset:256 sc1
.Lwtp1d_15:
	s_cbranch_vccnz .LBB0_223
	s_andn2_b64 vcc, exec, s[10:11]
	s_cbranch_vccnz .LBB0_222
	s_barrier
	s_branch .LBB0_222
